# MLA: lazy rescale of O (skip per-tile alpha rescale unless some row max grows by more than 2^8; mathematically identical softmax) on top of pipelined GEMM loops + regenerated MLA tile body
# speedup vs baseline: 1.0418x; 1.0095x over previous
.LBB0_1558:
	s_add_i32 s50, s46, -1
	v_min_u32_e32 v0, s50, v205
	v_mad_u64_u32 v[2:3], s[50:51], v0, s30, v[208:209]
	v_lshlrev_b32_e32 v0, 6, v0
	v_lshl_add_u64 v[4:5], v[0:1], 1, v[206:207]
	v_add_u32_e32 v0, 0xa800, v222
	s_add_i32 s47, s46, -4
	s_waitcnt vmcnt(7)
	ds_write_b128 v216, v[164:167] offset:43008
	s_waitcnt vmcnt(8)
	ds_write_b128 v217, v[160:163] offset:43008
	s_waitcnt vmcnt(7)
	ds_write_b128 v218, v[168:171] offset:43008
	s_waitcnt vmcnt(3)
	ds_write2_b64 v0, v[180:181], v[182:183] offset1:1
	v_add_u32_e32 v0, 0xca00, v222
	s_waitcnt vmcnt(1)
	ds_write2_b64 v0, v[188:189], v[190:191] offset1:1
	v_add_co_u32_e32 v6, vcc, 0x2000, v2
	s_nop 1
	v_addc_co_u32_e32 v7, vcc, 0, v3, vcc
	v_add_co_u32_e32 v8, vcc, 0x4000, v2
	s_nop 1
	v_addc_co_u32_e32 v9, vcc, 0, v3, vcc
	global_load_dwordx4 v[160:163], v[6:7], off
	global_load_dwordx4 v[168:171], v[8:9], off
	global_load_dwordx4 v[164:167], v[2:3], off
	global_load_dwordx4 v[180:183], v[4:5], off
	v_add_co_u32_e32 v2, vcc, 0x310000, v4
	s_nop 1
	v_addc_co_u32_e32 v3, vcc, 0, v5, vcc
	global_load_dwordx4 v[188:191], v[2:3], off
	s_cmp_ge_i32 s47, s43
	s_cbranch_scc1 .LBB0_1562
	ds_read_b128 v[4:7], v225
	ds_read_b128 v[8:11], v225 offset:12800
	ds_read_b128 v[12:15], v225 offset:32
	ds_read_b128 v[228:231], v225 offset:12832
	ds_read_b128 v[232:235], v225 offset:64
	ds_read_b128 v[236:239], v225 offset:12864
	ds_read_b128 v[240:243], v225 offset:96
	s_waitcnt lgkmcnt(6)
	v_mfma_f32_32x32x16_bf16 v[96:111], v[4:7], v[156:159], 0
	ds_read_b128 v[244:247], v225 offset:12896
	s_waitcnt lgkmcnt(6)
	v_mfma_f32_32x32x16_bf16 v[80:95], v[8:11], v[156:159], 0
	ds_read_b128 v[4:7], v225 offset:128
	s_waitcnt lgkmcnt(6)
	v_mfma_f32_32x32x16_bf16 v[96:111], v[12:15], v[152:155], v[96:111]
	ds_read_b128 v[8:11], v225 offset:12928
	s_waitcnt lgkmcnt(6)
	v_mfma_f32_32x32x16_bf16 v[80:95], v[228:231], v[152:155], v[80:95]
	ds_read_b128 v[12:15], v225 offset:160
	s_waitcnt lgkmcnt(6)
	v_mfma_f32_32x32x16_bf16 v[96:111], v[232:235], v[148:151], v[96:111]
	ds_read_b128 v[228:231], v225 offset:12960
	s_waitcnt lgkmcnt(6)
	v_mfma_f32_32x32x16_bf16 v[80:95], v[236:239], v[148:151], v[80:95]
	ds_read_b128 v[232:235], v225 offset:192
	s_waitcnt lgkmcnt(6)
	v_mfma_f32_32x32x16_bf16 v[96:111], v[240:243], v[144:147], v[96:111]
	ds_read_b128 v[236:239], v225 offset:12992
	s_waitcnt lgkmcnt(6)
	v_mfma_f32_32x32x16_bf16 v[80:95], v[244:247], v[144:147], v[80:95]
	ds_read_b128 v[240:243], v225 offset:224
	s_waitcnt lgkmcnt(6)
	v_mfma_f32_32x32x16_bf16 v[96:111], v[4:7], v[140:143], v[96:111]
	ds_read_b128 v[244:247], v225 offset:13024
	s_waitcnt lgkmcnt(6)
	v_mfma_f32_32x32x16_bf16 v[80:95], v[8:11], v[140:143], v[80:95]
	ds_read_b128 v[4:7], v225 offset:256
	s_waitcnt lgkmcnt(6)
	v_mfma_f32_32x32x16_bf16 v[96:111], v[12:15], v[136:139], v[96:111]
	ds_read_b128 v[8:11], v225 offset:13056
	s_waitcnt lgkmcnt(6)
	v_mfma_f32_32x32x16_bf16 v[80:95], v[228:231], v[136:139], v[80:95]
	ds_read_b128 v[12:15], v225 offset:288
	s_waitcnt lgkmcnt(6)
	v_mfma_f32_32x32x16_bf16 v[96:111], v[232:235], v[132:135], v[96:111]
	ds_read_b128 v[228:231], v225 offset:13088
	s_waitcnt lgkmcnt(6)
	v_mfma_f32_32x32x16_bf16 v[80:95], v[236:239], v[132:135], v[80:95]
	ds_read_b128 v[232:235], v225 offset:320
	s_waitcnt lgkmcnt(6)
	v_mfma_f32_32x32x16_bf16 v[96:111], v[240:243], v[128:131], v[96:111]
	ds_read_b128 v[236:239], v225 offset:13120
	s_waitcnt lgkmcnt(6)
	v_mfma_f32_32x32x16_bf16 v[80:95], v[244:247], v[128:131], v[80:95]
	ds_read_b128 v[240:243], v225 offset:352
	s_waitcnt lgkmcnt(6)
	v_mfma_f32_32x32x16_bf16 v[96:111], v[4:7], v[124:127], v[96:111]
	ds_read_b128 v[244:247], v225 offset:13152
	s_waitcnt lgkmcnt(6)
	v_mfma_f32_32x32x16_bf16 v[80:95], v[8:11], v[124:127], v[80:95]
	s_waitcnt lgkmcnt(5)
	v_mfma_f32_32x32x16_bf16 v[96:111], v[12:15], v[120:123], v[96:111]
	s_waitcnt lgkmcnt(4)
	v_mfma_f32_32x32x16_bf16 v[80:95], v[228:231], v[120:123], v[80:95]
	s_waitcnt lgkmcnt(3)
	v_mfma_f32_32x32x16_bf16 v[96:111], v[232:235], v[116:119], v[96:111]
	s_waitcnt lgkmcnt(2)
	v_mfma_f32_32x32x16_bf16 v[80:95], v[236:239], v[116:119], v[80:95]
	s_waitcnt lgkmcnt(1)
	v_mfma_f32_32x32x16_bf16 v[96:111], v[240:243], v[112:115], v[96:111]
	s_waitcnt lgkmcnt(0)
	v_mfma_f32_32x32x16_bf16 v[80:95], v[244:247], v[112:115], v[80:95]
	v_and_b32_e32 v248, 64, v210
	v_xor_b32_e32 v249, 32, v210
	v_add_u32_e32 v248, 64, v248
	v_cmp_lt_i32_e32 vcc, v249, v248
	ds_read_b64 v[228:229], v223 offset:25600
	ds_read_b64 v[230:231], v223 offset:25616
	ds_read_b64 v[232:233], v223 offset:29952
	ds_read_b64 v[234:235], v223 offset:29968
	ds_read_b64 v[236:237], v223 offset:34304
	ds_read_b64 v[238:239], v223 offset:34320
	ds_read_b64 v[240:241], v223 offset:38656
	ds_read_b64 v[242:243], v223 offset:38672
	ds_read_b64 v[244:245], v223 offset:25632
	ds_read_b64 v[246:247], v223 offset:25648
	v_cndmask_b32_e32 v249, v210, v249, vcc
	v_lshlrev_b32_e32 v249, 2, v249
	s_nop 1
	v_max_f32_e32 v0, v96, v80
	v_max3_f32 v0, v0, v97, v81
	v_max3_f32 v0, v0, v98, v82
	v_max3_f32 v0, v0, v99, v83
	v_max3_f32 v0, v0, v100, v84
	v_max3_f32 v0, v0, v101, v85
	v_max3_f32 v0, v0, v102, v86
	v_max3_f32 v0, v0, v103, v87
	v_max3_f32 v0, v0, v104, v88
	v_max3_f32 v0, v0, v105, v89
	v_max3_f32 v0, v0, v106, v90
	v_max3_f32 v0, v0, v107, v91
	v_max3_f32 v0, v0, v108, v92
	v_max3_f32 v0, v0, v109, v93
	v_max3_f32 v0, v0, v110, v94
	v_max3_f32 v0, v0, v111, v95
	ds_bpermute_b32 v248, v249, v0
	s_waitcnt lgkmcnt(0)
	v_max_f32_e32 v0, v0, v248
	v_max_f32_e32 v248, v226, v226
	v_max_f32_e32 v0, v0, v0
	v_sub_f32_e32 v249, v0, v248
	v_cmp_lt_f32_e32 vcc, 0x41000000, v249
	s_cbranch_vccz .Lmla_keep_a
	v_max_f32_e32 v2, v248, v0
	v_sub_f32_e32 v0, v226, v2
	v_exp_f32_e32 v0, v0
	s_nop 0
	v_pk_mul_f32 v[78:79], v[78:79], v[0:1] op_sel_hi:[1,0]
	v_pk_mul_f32 v[76:77], v[76:77], v[0:1] op_sel_hi:[1,0]
	v_pk_mul_f32 v[74:75], v[74:75], v[0:1] op_sel_hi:[1,0]
	v_pk_mul_f32 v[72:73], v[72:73], v[0:1] op_sel_hi:[1,0]
	v_pk_mul_f32 v[70:71], v[70:71], v[0:1] op_sel_hi:[1,0]
	v_pk_mul_f32 v[68:69], v[68:69], v[0:1] op_sel_hi:[1,0]
	v_pk_mul_f32 v[66:67], v[66:67], v[0:1] op_sel_hi:[1,0]
	v_pk_mul_f32 v[64:65], v[64:65], v[0:1] op_sel_hi:[1,0]
	v_pk_mul_f32 v[62:63], v[62:63], v[0:1] op_sel_hi:[1,0]
	v_pk_mul_f32 v[60:61], v[60:61], v[0:1] op_sel_hi:[1,0]
	v_pk_mul_f32 v[58:59], v[58:59], v[0:1] op_sel_hi:[1,0]
	v_pk_mul_f32 v[56:57], v[56:57], v[0:1] op_sel_hi:[1,0]
	v_pk_mul_f32 v[54:55], v[54:55], v[0:1] op_sel_hi:[1,0]
	v_pk_mul_f32 v[52:53], v[52:53], v[0:1] op_sel_hi:[1,0]
	v_pk_mul_f32 v[50:51], v[50:51], v[0:1] op_sel_hi:[1,0]
	v_pk_mul_f32 v[48:49], v[48:49], v[0:1] op_sel_hi:[1,0]
	v_pk_mul_f32 v[46:47], v[46:47], v[0:1] op_sel_hi:[1,0]
	v_pk_mul_f32 v[44:45], v[44:45], v[0:1] op_sel_hi:[1,0]
	v_pk_mul_f32 v[42:43], v[42:43], v[0:1] op_sel_hi:[1,0]
	v_pk_mul_f32 v[40:41], v[40:41], v[0:1] op_sel_hi:[1,0]
	v_pk_mul_f32 v[38:39], v[38:39], v[0:1] op_sel_hi:[1,0]
	v_pk_mul_f32 v[36:37], v[36:37], v[0:1] op_sel_hi:[1,0]
	v_pk_mul_f32 v[34:35], v[34:35], v[0:1] op_sel_hi:[1,0]
	v_pk_mul_f32 v[32:33], v[32:33], v[0:1] op_sel_hi:[1,0]
	v_pk_mul_f32 v[30:31], v[30:31], v[0:1] op_sel_hi:[1,0]
	v_pk_mul_f32 v[28:29], v[28:29], v[0:1] op_sel_hi:[1,0]
	v_pk_mul_f32 v[26:27], v[26:27], v[0:1] op_sel_hi:[1,0]
	v_pk_mul_f32 v[24:25], v[24:25], v[0:1] op_sel_hi:[1,0]
	v_pk_mul_f32 v[22:23], v[22:23], v[0:1] op_sel_hi:[1,0]
	v_pk_mul_f32 v[20:21], v[20:21], v[0:1] op_sel_hi:[1,0]
	v_pk_mul_f32 v[18:19], v[18:19], v[0:1] op_sel_hi:[1,0]
	v_pk_mul_f32 v[16:17], v[16:17], v[0:1] op_sel_hi:[1,0]
	s_branch .Lmla_join_a
	.Lmla_keep_a:
	v_mov_b32_e32 v2, v248
	v_mov_b32_e32 v0, 1.0
	.Lmla_join_a:
	v_sub_f32_e32 v248, v96, v2
	v_exp_f32_e32 v96, v248
	v_sub_f32_e32 v249, v97, v2
	v_exp_f32_e32 v97, v249
	v_sub_f32_e32 v248, v98, v2
	v_exp_f32_e32 v98, v248
	v_sub_f32_e32 v249, v99, v2
	v_exp_f32_e32 v99, v249
	v_sub_f32_e32 v248, v100, v2
	v_exp_f32_e32 v100, v248
	v_sub_f32_e32 v249, v101, v2
	v_exp_f32_e32 v101, v249
	v_sub_f32_e32 v248, v102, v2
	v_exp_f32_e32 v102, v248
	v_sub_f32_e32 v249, v103, v2
	v_exp_f32_e32 v103, v249
	s_nop 0
	v_cvt_pk_bf16_f32 v8, v96, v97
	v_cvt_pk_bf16_f32 v9, v98, v99
	v_cvt_pk_bf16_f32 v10, v100, v101
	v_cvt_pk_bf16_f32 v11, v102, v103
	v_sub_f32_e32 v248, v104, v2
	v_exp_f32_e32 v104, v248
	v_mfma_f32_32x32x16_bf16 v[64:79], v[228:231], v[8:11], v[64:79]
	ds_read_b64 v[228:229], v223 offset:29984
	ds_read_b64 v[230:231], v223 offset:30000
	v_sub_f32_e32 v249, v105, v2
	v_exp_f32_e32 v105, v249
	v_mfma_f32_32x32x16_bf16 v[48:63], v[232:235], v[8:11], v[48:63]
	ds_read_b64 v[232:233], v223 offset:34336
	ds_read_b64 v[234:235], v223 offset:34352
	v_sub_f32_e32 v248, v106, v2
	v_exp_f32_e32 v106, v248
	v_sub_f32_e32 v249, v107, v2
	v_exp_f32_e32 v107, v249
	v_mfma_f32_32x32x16_bf16 v[32:47], v[236:239], v[8:11], v[32:47]
	ds_read_b64 v[236:237], v223 offset:38688
	ds_read_b64 v[238:239], v223 offset:38704
	v_sub_f32_e32 v248, v108, v2
	v_exp_f32_e32 v108, v248
	v_sub_f32_e32 v249, v109, v2
	v_exp_f32_e32 v109, v249
	v_mfma_f32_32x32x16_bf16 v[16:31], v[240:243], v[8:11], v[16:31]
	ds_read_b64 v[240:241], v223 offset:25664
	ds_read_b64 v[242:243], v223 offset:25680
	v_sub_f32_e32 v248, v110, v2
	v_exp_f32_e32 v110, v248
	v_sub_f32_e32 v249, v111, v2
	v_exp_f32_e32 v111, v249
	s_nop 0
	v_cvt_pk_bf16_f32 v4, v104, v105
	v_cvt_pk_bf16_f32 v5, v106, v107
	v_cvt_pk_bf16_f32 v6, v108, v109
	v_cvt_pk_bf16_f32 v7, v110, v111
	s_nop 1
	v_mfma_f32_32x32x16_bf16 v[64:79], v[244:247], v[4:7], v[64:79]
	ds_read_b64 v[244:245], v223 offset:30016
	ds_read_b64 v[246:247], v223 offset:30032
	v_sub_f32_e32 v248, v80, v2
	v_exp_f32_e32 v80, v248
	v_sub_f32_e32 v249, v81, v2
	v_exp_f32_e32 v81, v249
	s_waitcnt lgkmcnt(8)
	v_mfma_f32_32x32x16_bf16 v[48:63], v[228:231], v[4:7], v[48:63]
	ds_read_b64 v[228:229], v223 offset:34368
	ds_read_b64 v[230:231], v223 offset:34384
	v_sub_f32_e32 v248, v82, v2
	v_exp_f32_e32 v82, v248
	v_sub_f32_e32 v249, v83, v2
	v_exp_f32_e32 v83, v249
	s_waitcnt lgkmcnt(8)
	v_mfma_f32_32x32x16_bf16 v[32:47], v[232:235], v[4:7], v[32:47]
	ds_read_b64 v[232:233], v223 offset:38720
	ds_read_b64 v[234:235], v223 offset:38736
	v_sub_f32_e32 v248, v84, v2
	v_exp_f32_e32 v84, v248
	v_sub_f32_e32 v249, v85, v2
	v_exp_f32_e32 v85, v249
	s_waitcnt lgkmcnt(8)
	v_mfma_f32_32x32x16_bf16 v[16:31], v[236:239], v[4:7], v[16:31]
	ds_read_b64 v[236:237], v223 offset:25696
	ds_read_b64 v[238:239], v223 offset:25712
	v_sub_f32_e32 v248, v86, v2
	v_exp_f32_e32 v86, v248
	v_sub_f32_e32 v249, v87, v2
	v_exp_f32_e32 v87, v249
	s_nop 0
	v_cvt_pk_bf16_f32 v12, v80, v81
	v_cvt_pk_bf16_f32 v13, v82, v83
	v_cvt_pk_bf16_f32 v14, v84, v85
	v_cvt_pk_bf16_f32 v15, v86, v87
	s_nop 1
	s_waitcnt lgkmcnt(8)
	v_mfma_f32_32x32x16_bf16 v[64:79], v[240:243], v[12:15], v[64:79]
	ds_read_b64 v[240:241], v223 offset:30048
	ds_read_b64 v[242:243], v223 offset:30064
	v_sub_f32_e32 v248, v88, v2
	v_exp_f32_e32 v88, v248
	v_sub_f32_e32 v249, v89, v2
	v_exp_f32_e32 v89, v249
	s_waitcnt lgkmcnt(8)
	v_mfma_f32_32x32x16_bf16 v[48:63], v[244:247], v[12:15], v[48:63]
	ds_read_b64 v[244:245], v223 offset:34400
	ds_read_b64 v[246:247], v223 offset:34416
	v_sub_f32_e32 v248, v90, v2
	v_exp_f32_e32 v90, v248
	v_sub_f32_e32 v249, v91, v2
	v_exp_f32_e32 v91, v249
	s_waitcnt lgkmcnt(8)
	v_mfma_f32_32x32x16_bf16 v[32:47], v[228:231], v[12:15], v[32:47]
	ds_read_b64 v[228:229], v223 offset:38752
	ds_read_b64 v[230:231], v223 offset:38768
	v_sub_f32_e32 v248, v92, v2
	v_exp_f32_e32 v92, v248
	v_sub_f32_e32 v249, v93, v2
	v_exp_f32_e32 v93, v249
	s_waitcnt lgkmcnt(8)
	v_mfma_f32_32x32x16_bf16 v[16:31], v[232:235], v[12:15], v[16:31]
	v_sub_f32_e32 v248, v94, v2
	v_exp_f32_e32 v94, v248
	v_sub_f32_e32 v249, v95, v2
	v_exp_f32_e32 v95, v249
	s_nop 0
	v_cvt_pk_bf16_f32 v8, v88, v89
	v_cvt_pk_bf16_f32 v9, v90, v91
	v_cvt_pk_bf16_f32 v10, v92, v93
	v_cvt_pk_bf16_f32 v11, v94, v95
	s_nop 1
	s_waitcnt lgkmcnt(6)
	v_mfma_f32_32x32x16_bf16 v[64:79], v[236:239], v[8:11], v[64:79]
	v_add_f32_e32 v3, v80, v96
	v_add_f32_e32 v248, v81, v97
	v_add_f32_e32 v3, v248, v3
	v_add_f32_e32 v249, v82, v98
	v_add_f32_e32 v3, v249, v3
	v_add_f32_e32 v248, v83, v99
	v_add_f32_e32 v3, v248, v3
	v_add_f32_e32 v249, v84, v100
	s_waitcnt lgkmcnt(4)
	v_mfma_f32_32x32x16_bf16 v[48:63], v[240:243], v[8:11], v[48:63]
	v_add_f32_e32 v3, v249, v3
	v_add_f32_e32 v248, v85, v101
	v_add_f32_e32 v3, v248, v3
	v_add_f32_e32 v249, v86, v102
	v_add_f32_e32 v3, v249, v3
	v_add_f32_e32 v248, v87, v103
	v_add_f32_e32 v3, v248, v3
	v_add_f32_e32 v249, v88, v104
	s_waitcnt lgkmcnt(2)
	v_mfma_f32_32x32x16_bf16 v[32:47], v[244:247], v[8:11], v[32:47]
	v_add_f32_e32 v3, v249, v3
	v_add_f32_e32 v248, v89, v105
	v_add_f32_e32 v3, v248, v3
	v_add_f32_e32 v249, v90, v106
	v_add_f32_e32 v3, v249, v3
	v_add_f32_e32 v248, v91, v107
	v_add_f32_e32 v3, v248, v3
	v_add_f32_e32 v249, v92, v108
	s_waitcnt lgkmcnt(0)
	v_mfma_f32_32x32x16_bf16 v[16:31], v[228:231], v[8:11], v[16:31]
	v_add_f32_e32 v3, v249, v3
	v_add_f32_e32 v248, v93, v109
	v_add_f32_e32 v3, v248, v3
	v_add_f32_e32 v249, v94, v110
	v_add_f32_e32 v3, v249, v3
	v_add_f32_e32 v248, v95, v111
	v_add_f32_e32 v3, v248, v3
	v_fmac_f32_e32 v3, v221, v0
	v_mov_b32_e32 v221, v3
	s_branch .LBB0_1563

; #define MLA_LOAD(S, KT) do { const int kc_ = (KT) < nkt ? (KT) : nkt - 1; const bf16_t* Kn_ = Kg + (size_t)kc_ * 64 * 192 + (size_t)tid * 8; const bf16_t* Vn_ = Vg0 + kc_ * 64; \
;         S##k0 = *(const uint4*)(Kn_); S##k1 = *(const uint4*)(Kn_ + 4096); S##k2 = *(const uint4*)(Kn_ + 8192); \
;         S##v0 = *(const uint4*)(Vn_); S##v1 = *(const uint4*)(Vn_ + (size_t)64 * NKEY); } while (0)
; __device__ __forceinline__ void mla_item(const Params& P, int h, int qrow0, int keyrow0, int my_nkt_in, int nkt, char* lds) {
;     ...
;         __syncthreads();
;         MLA_STORE(y, 0);
;         __builtin_amdgcn_sched_barrier(0);
;         MLA_LOAD(y, kt2 + 4);
;         __builtin_amdgcn_sched_barrier(0);
;         MLA_COMP(kt2 + 1, 1);
.LBB0_1563:
	v_min_u32_e32 v0, s46, v205
	v_mad_u64_u32 v[4:5], s[50:51], v0, s30, v[208:209]
	v_lshlrev_b32_e32 v0, 6, v0
	s_waitcnt lgkmcnt(0)
	s_barrier
	ds_write_b128 v216, v[172:175]
	ds_write_b128 v217, v[184:187]
	ds_write_b128 v218, v[192:195]
	v_lshl_add_u64 v[6:7], v[0:1], 1, v[206:207]
	ds_write2_b64 v219, v[176:177], v[178:179] offset1:1
	s_waitcnt vmcnt(5)
	ds_write2_b64 v220, v[196:197], v[198:199] offset1:1
	v_add_co_u32_e32 v8, vcc, 0x2000, v4
	s_nop 1
	v_addc_co_u32_e32 v9, vcc, 0, v5, vcc
	v_add_co_u32_e32 v10, vcc, 0x4000, v4
	s_nop 1
	v_addc_co_u32_e32 v11, vcc, 0, v5, vcc
	global_load_dwordx4 v[184:187], v[8:9], off
	global_load_dwordx4 v[192:195], v[10:11], off
	global_load_dwordx4 v[172:175], v[4:5], off
	global_load_dwordx4 v[176:179], v[6:7], off
	v_add_co_u32_e32 v4, vcc, 0x310000, v6
	s_nop 1
	v_addc_co_u32_e32 v5, vcc, 0, v7, vcc
	global_load_dwordx4 v[196:199], v[4:5], off
	s_add_i32 s47, s47, 1
	s_cmp_ge_i32 s47, s43
	s_cbranch_scc1 .LBB0_1556
	ds_read_b128 v[4:7], v225 offset:43008
	ds_read_b128 v[8:11], v225 offset:55808
	ds_read_b128 v[12:15], v225 offset:43040
	ds_read_b128 v[228:231], v225 offset:55840
	ds_read_b128 v[232:235], v225 offset:43072
	ds_read_b128 v[236:239], v225 offset:55872
	ds_read_b128 v[240:243], v225 offset:43104
	s_waitcnt lgkmcnt(6)
	v_mfma_f32_32x32x16_bf16 v[96:111], v[4:7], v[156:159], 0
	ds_read_b128 v[244:247], v225 offset:55904
	s_waitcnt lgkmcnt(6)
	v_mfma_f32_32x32x16_bf16 v[80:95], v[8:11], v[156:159], 0
	ds_read_b128 v[4:7], v225 offset:43136
	s_waitcnt lgkmcnt(6)
	v_mfma_f32_32x32x16_bf16 v[96:111], v[12:15], v[152:155], v[96:111]
	ds_read_b128 v[8:11], v225 offset:55936
	s_waitcnt lgkmcnt(6)
	v_mfma_f32_32x32x16_bf16 v[80:95], v[228:231], v[152:155], v[80:95]
	ds_read_b128 v[12:15], v225 offset:43168
	s_waitcnt lgkmcnt(6)
	v_mfma_f32_32x32x16_bf16 v[96:111], v[232:235], v[148:151], v[96:111]
	ds_read_b128 v[228:231], v225 offset:55968
	s_waitcnt lgkmcnt(6)
	v_mfma_f32_32x32x16_bf16 v[80:95], v[236:239], v[148:151], v[80:95]
	ds_read_b128 v[232:235], v225 offset:43200
	s_waitcnt lgkmcnt(6)
	v_mfma_f32_32x32x16_bf16 v[96:111], v[240:243], v[144:147], v[96:111]
	ds_read_b128 v[236:239], v225 offset:56000
	s_waitcnt lgkmcnt(6)
	v_mfma_f32_32x32x16_bf16 v[80:95], v[244:247], v[144:147], v[80:95]
	ds_read_b128 v[240:243], v225 offset:43232
	s_waitcnt lgkmcnt(6)
	v_mfma_f32_32x32x16_bf16 v[96:111], v[4:7], v[140:143], v[96:111]
	ds_read_b128 v[244:247], v225 offset:56032
	s_waitcnt lgkmcnt(6)
	v_mfma_f32_32x32x16_bf16 v[80:95], v[8:11], v[140:143], v[80:95]
	ds_read_b128 v[4:7], v225 offset:43264
	s_waitcnt lgkmcnt(6)
	v_mfma_f32_32x32x16_bf16 v[96:111], v[12:15], v[136:139], v[96:111]
	ds_read_b128 v[8:11], v225 offset:56064
	s_waitcnt lgkmcnt(6)
	v_mfma_f32_32x32x16_bf16 v[80:95], v[228:231], v[136:139], v[80:95]
	ds_read_b128 v[12:15], v225 offset:43296
	s_waitcnt lgkmcnt(6)
	v_mfma_f32_32x32x16_bf16 v[96:111], v[232:235], v[132:135], v[96:111]
	ds_read_b128 v[228:231], v225 offset:56096
	s_waitcnt lgkmcnt(6)
	v_mfma_f32_32x32x16_bf16 v[80:95], v[236:239], v[132:135], v[80:95]
	ds_read_b128 v[232:235], v225 offset:43328
	s_waitcnt lgkmcnt(6)
	v_mfma_f32_32x32x16_bf16 v[96:111], v[240:243], v[128:131], v[96:111]
	ds_read_b128 v[236:239], v225 offset:56128
	s_waitcnt lgkmcnt(6)
	v_mfma_f32_32x32x16_bf16 v[80:95], v[244:247], v[128:131], v[80:95]
	ds_read_b128 v[240:243], v225 offset:43360
	s_waitcnt lgkmcnt(6)
	v_mfma_f32_32x32x16_bf16 v[96:111], v[4:7], v[124:127], v[96:111]
	ds_read_b128 v[244:247], v225 offset:56160
	s_waitcnt lgkmcnt(6)
	v_mfma_f32_32x32x16_bf16 v[80:95], v[8:11], v[124:127], v[80:95]
	s_waitcnt lgkmcnt(5)
	v_mfma_f32_32x32x16_bf16 v[96:111], v[12:15], v[120:123], v[96:111]
	s_waitcnt lgkmcnt(4)
	v_mfma_f32_32x32x16_bf16 v[80:95], v[228:231], v[120:123], v[80:95]
	s_waitcnt lgkmcnt(3)
	v_mfma_f32_32x32x16_bf16 v[96:111], v[232:235], v[116:119], v[96:111]
	s_waitcnt lgkmcnt(2)
	v_mfma_f32_32x32x16_bf16 v[80:95], v[236:239], v[116:119], v[80:95]
	s_waitcnt lgkmcnt(1)
	v_mfma_f32_32x32x16_bf16 v[96:111], v[240:243], v[112:115], v[96:111]
	s_waitcnt lgkmcnt(0)
	v_mfma_f32_32x32x16_bf16 v[80:95], v[244:247], v[112:115], v[80:95]
	v_and_b32_e32 v248, 64, v210
	v_xor_b32_e32 v249, 32, v210
	v_add_u32_e32 v248, 64, v248
	v_cmp_lt_i32_e32 vcc, v249, v248
	ds_read_b64 v[228:229], v224 offset:0
	ds_read_b64 v[230:231], v224 offset:16
	ds_read_b64 v[232:233], v224 offset:4352
	ds_read_b64 v[234:235], v224 offset:4368
	ds_read_b64 v[236:237], v224 offset:8704
	ds_read_b64 v[238:239], v224 offset:8720
	ds_read_b64 v[240:241], v224 offset:13056
	ds_read_b64 v[242:243], v224 offset:13072
	ds_read_b64 v[244:245], v224 offset:32
	ds_read_b64 v[246:247], v224 offset:48
	v_cndmask_b32_e32 v249, v210, v249, vcc
	v_lshlrev_b32_e32 v249, 2, v249
	s_nop 1
	v_max_f32_e32 v0, v96, v80
	v_max3_f32 v0, v0, v97, v81
	v_max3_f32 v0, v0, v98, v82
	v_max3_f32 v0, v0, v99, v83
	v_max3_f32 v0, v0, v100, v84
	v_max3_f32 v0, v0, v101, v85
	v_max3_f32 v0, v0, v102, v86
	v_max3_f32 v0, v0, v103, v87
	v_max3_f32 v0, v0, v104, v88
	v_max3_f32 v0, v0, v105, v89
	v_max3_f32 v0, v0, v106, v90
	v_max3_f32 v0, v0, v107, v91
	v_max3_f32 v0, v0, v108, v92
	v_max3_f32 v0, v0, v109, v93
	v_max3_f32 v0, v0, v110, v94
	v_max3_f32 v0, v0, v111, v95
	ds_bpermute_b32 v248, v249, v0
	s_waitcnt lgkmcnt(0)
	v_max_f32_e32 v0, v0, v248
	v_max_f32_e32 v248, v2, v2
	v_max_f32_e32 v0, v0, v0
	v_sub_f32_e32 v249, v0, v248
	v_cmp_lt_f32_e32 vcc, 0x41000000, v249
	s_cbranch_vccz .Lmla_keep_b
	v_max_f32_e32 v226, v248, v0
	v_sub_f32_e32 v0, v2, v226
	v_exp_f32_e32 v0, v0
	s_nop 0
	v_pk_mul_f32 v[78:79], v[78:79], v[0:1] op_sel_hi:[1,0]
	v_pk_mul_f32 v[76:77], v[76:77], v[0:1] op_sel_hi:[1,0]
	v_pk_mul_f32 v[74:75], v[74:75], v[0:1] op_sel_hi:[1,0]
	v_pk_mul_f32 v[72:73], v[72:73], v[0:1] op_sel_hi:[1,0]
	v_pk_mul_f32 v[70:71], v[70:71], v[0:1] op_sel_hi:[1,0]
	v_pk_mul_f32 v[68:69], v[68:69], v[0:1] op_sel_hi:[1,0]
	v_pk_mul_f32 v[66:67], v[66:67], v[0:1] op_sel_hi:[1,0]
	v_pk_mul_f32 v[64:65], v[64:65], v[0:1] op_sel_hi:[1,0]
	v_pk_mul_f32 v[62:63], v[62:63], v[0:1] op_sel_hi:[1,0]
	v_pk_mul_f32 v[60:61], v[60:61], v[0:1] op_sel_hi:[1,0]
	v_pk_mul_f32 v[58:59], v[58:59], v[0:1] op_sel_hi:[1,0]
	v_pk_mul_f32 v[56:57], v[56:57], v[0:1] op_sel_hi:[1,0]
	v_pk_mul_f32 v[54:55], v[54:55], v[0:1] op_sel_hi:[1,0]
	v_pk_mul_f32 v[52:53], v[52:53], v[0:1] op_sel_hi:[1,0]
	v_pk_mul_f32 v[50:51], v[50:51], v[0:1] op_sel_hi:[1,0]
	v_pk_mul_f32 v[48:49], v[48:49], v[0:1] op_sel_hi:[1,0]
	v_pk_mul_f32 v[46:47], v[46:47], v[0:1] op_sel_hi:[1,0]
	v_pk_mul_f32 v[44:45], v[44:45], v[0:1] op_sel_hi:[1,0]
	v_pk_mul_f32 v[42:43], v[42:43], v[0:1] op_sel_hi:[1,0]
	v_pk_mul_f32 v[40:41], v[40:41], v[0:1] op_sel_hi:[1,0]
	v_pk_mul_f32 v[38:39], v[38:39], v[0:1] op_sel_hi:[1,0]
	v_pk_mul_f32 v[36:37], v[36:37], v[0:1] op_sel_hi:[1,0]
	v_pk_mul_f32 v[34:35], v[34:35], v[0:1] op_sel_hi:[1,0]
	v_pk_mul_f32 v[32:33], v[32:33], v[0:1] op_sel_hi:[1,0]
	v_pk_mul_f32 v[30:31], v[30:31], v[0:1] op_sel_hi:[1,0]
	v_pk_mul_f32 v[28:29], v[28:29], v[0:1] op_sel_hi:[1,0]
	v_pk_mul_f32 v[26:27], v[26:27], v[0:1] op_sel_hi:[1,0]
	v_pk_mul_f32 v[24:25], v[24:25], v[0:1] op_sel_hi:[1,0]
	v_pk_mul_f32 v[22:23], v[22:23], v[0:1] op_sel_hi:[1,0]
	v_pk_mul_f32 v[20:21], v[20:21], v[0:1] op_sel_hi:[1,0]
	v_pk_mul_f32 v[18:19], v[18:19], v[0:1] op_sel_hi:[1,0]
	v_pk_mul_f32 v[16:17], v[16:17], v[0:1] op_sel_hi:[1,0]
	s_branch .Lmla_join_b
	.Lmla_keep_b:
	v_mov_b32_e32 v226, v248
	v_mov_b32_e32 v0, 1.0
	.Lmla_join_b:
	v_sub_f32_e32 v248, v96, v226
	v_exp_f32_e32 v96, v248
	v_sub_f32_e32 v249, v97, v226
	v_exp_f32_e32 v97, v249
	v_sub_f32_e32 v248, v98, v226
	v_exp_f32_e32 v98, v248
	v_sub_f32_e32 v249, v99, v226
	v_exp_f32_e32 v99, v249
	v_sub_f32_e32 v248, v100, v226
	v_exp_f32_e32 v100, v248
	v_sub_f32_e32 v249, v101, v226
	v_exp_f32_e32 v101, v249
	v_sub_f32_e32 v248, v102, v226
	v_exp_f32_e32 v102, v248
	v_sub_f32_e32 v249, v103, v226
	v_exp_f32_e32 v103, v249
	s_nop 0
	v_cvt_pk_bf16_f32 v8, v96, v97
	v_cvt_pk_bf16_f32 v9, v98, v99
	v_cvt_pk_bf16_f32 v10, v100, v101
	v_cvt_pk_bf16_f32 v11, v102, v103
	v_sub_f32_e32 v248, v104, v226
	v_exp_f32_e32 v104, v248
	v_mfma_f32_32x32x16_bf16 v[64:79], v[228:231], v[8:11], v[64:79]
	ds_read_b64 v[228:229], v224 offset:4384
	ds_read_b64 v[230:231], v224 offset:4400
	v_sub_f32_e32 v249, v105, v226
	v_exp_f32_e32 v105, v249
	v_mfma_f32_32x32x16_bf16 v[48:63], v[232:235], v[8:11], v[48:63]
	ds_read_b64 v[232:233], v224 offset:8736
	ds_read_b64 v[234:235], v224 offset:8752
	v_sub_f32_e32 v248, v106, v226
	v_exp_f32_e32 v106, v248
	v_sub_f32_e32 v249, v107, v226
	v_exp_f32_e32 v107, v249
	v_mfma_f32_32x32x16_bf16 v[32:47], v[236:239], v[8:11], v[32:47]
	ds_read_b64 v[236:237], v224 offset:13088
	ds_read_b64 v[238:239], v224 offset:13104
	v_sub_f32_e32 v248, v108, v226
	v_exp_f32_e32 v108, v248
	v_sub_f32_e32 v249, v109, v226
	v_exp_f32_e32 v109, v249
	v_mfma_f32_32x32x16_bf16 v[16:31], v[240:243], v[8:11], v[16:31]
	ds_read_b64 v[240:241], v224 offset:64
	ds_read_b64 v[242:243], v224 offset:80
	v_sub_f32_e32 v248, v110, v226
	v_exp_f32_e32 v110, v248
	v_sub_f32_e32 v249, v111, v226
	v_exp_f32_e32 v111, v249
	s_nop 0
	v_cvt_pk_bf16_f32 v4, v104, v105
	v_cvt_pk_bf16_f32 v5, v106, v107
	v_cvt_pk_bf16_f32 v6, v108, v109
	v_cvt_pk_bf16_f32 v7, v110, v111
	s_nop 1
	v_mfma_f32_32x32x16_bf16 v[64:79], v[244:247], v[4:7], v[64:79]
	ds_read_b64 v[244:245], v224 offset:4416
	ds_read_b64 v[246:247], v224 offset:4432
	v_sub_f32_e32 v248, v80, v226
	v_exp_f32_e32 v80, v248
	v_sub_f32_e32 v249, v81, v226
	v_exp_f32_e32 v81, v249
	s_waitcnt lgkmcnt(8)
	v_mfma_f32_32x32x16_bf16 v[48:63], v[228:231], v[4:7], v[48:63]
	ds_read_b64 v[228:229], v224 offset:8768
	ds_read_b64 v[230:231], v224 offset:8784
	v_sub_f32_e32 v248, v82, v226
	v_exp_f32_e32 v82, v248
	v_sub_f32_e32 v249, v83, v226
	v_exp_f32_e32 v83, v249
	s_waitcnt lgkmcnt(8)
	v_mfma_f32_32x32x16_bf16 v[32:47], v[232:235], v[4:7], v[32:47]
	ds_read_b64 v[232:233], v224 offset:13120
	ds_read_b64 v[234:235], v224 offset:13136
	v_sub_f32_e32 v248, v84, v226
	v_exp_f32_e32 v84, v248
	v_sub_f32_e32 v249, v85, v226
	v_exp_f32_e32 v85, v249
	s_waitcnt lgkmcnt(8)
	v_mfma_f32_32x32x16_bf16 v[16:31], v[236:239], v[4:7], v[16:31]
	ds_read_b64 v[236:237], v224 offset:96
	ds_read_b64 v[238:239], v224 offset:112
	v_sub_f32_e32 v248, v86, v226
	v_exp_f32_e32 v86, v248
	v_sub_f32_e32 v249, v87, v226
	v_exp_f32_e32 v87, v249
	s_nop 0
	v_cvt_pk_bf16_f32 v12, v80, v81
	v_cvt_pk_bf16_f32 v13, v82, v83
	v_cvt_pk_bf16_f32 v14, v84, v85
	v_cvt_pk_bf16_f32 v15, v86, v87
	s_nop 1
	s_waitcnt lgkmcnt(8)
	v_mfma_f32_32x32x16_bf16 v[64:79], v[240:243], v[12:15], v[64:79]
	ds_read_b64 v[240:241], v224 offset:4448
	ds_read_b64 v[242:243], v224 offset:4464
	v_sub_f32_e32 v248, v88, v226
	v_exp_f32_e32 v88, v248
	v_sub_f32_e32 v249, v89, v226
	v_exp_f32_e32 v89, v249
	s_waitcnt lgkmcnt(8)
	v_mfma_f32_32x32x16_bf16 v[48:63], v[244:247], v[12:15], v[48:63]
	ds_read_b64 v[244:245], v224 offset:8800
	ds_read_b64 v[246:247], v224 offset:8816
	v_sub_f32_e32 v248, v90, v226
	v_exp_f32_e32 v90, v248
	v_sub_f32_e32 v249, v91, v226
	v_exp_f32_e32 v91, v249
	s_waitcnt lgkmcnt(8)
	v_mfma_f32_32x32x16_bf16 v[32:47], v[228:231], v[12:15], v[32:47]
	ds_read_b64 v[228:229], v224 offset:13152
	ds_read_b64 v[230:231], v224 offset:13168
	v_sub_f32_e32 v248, v92, v226
	v_exp_f32_e32 v92, v248
	v_sub_f32_e32 v249, v93, v226
	v_exp_f32_e32 v93, v249
	s_waitcnt lgkmcnt(8)
	v_mfma_f32_32x32x16_bf16 v[16:31], v[232:235], v[12:15], v[16:31]
	v_sub_f32_e32 v248, v94, v226
	v_exp_f32_e32 v94, v248
	v_sub_f32_e32 v249, v95, v226
	v_exp_f32_e32 v95, v249
	s_nop 0
	v_cvt_pk_bf16_f32 v8, v88, v89
	v_cvt_pk_bf16_f32 v9, v90, v91
	v_cvt_pk_bf16_f32 v10, v92, v93
	v_cvt_pk_bf16_f32 v11, v94, v95
	s_nop 1
	s_waitcnt lgkmcnt(6)
	v_mfma_f32_32x32x16_bf16 v[64:79], v[236:239], v[8:11], v[64:79]
	v_add_f32_e32 v3, v80, v96
	v_add_f32_e32 v248, v81, v97
	v_add_f32_e32 v3, v248, v3
	v_add_f32_e32 v249, v82, v98
	v_add_f32_e32 v3, v249, v3
	v_add_f32_e32 v248, v83, v99
	v_add_f32_e32 v3, v248, v3
	v_add_f32_e32 v249, v84, v100
	s_waitcnt lgkmcnt(4)
	v_mfma_f32_32x32x16_bf16 v[48:63], v[240:243], v[8:11], v[48:63]
	v_add_f32_e32 v3, v249, v3
	v_add_f32_e32 v248, v85, v101
	v_add_f32_e32 v3, v248, v3
	v_add_f32_e32 v249, v86, v102
	v_add_f32_e32 v3, v249, v3
	v_add_f32_e32 v248, v87, v103
	v_add_f32_e32 v3, v248, v3
	v_add_f32_e32 v249, v88, v104
	s_waitcnt lgkmcnt(2)
	v_mfma_f32_32x32x16_bf16 v[32:47], v[244:247], v[8:11], v[32:47]
	v_add_f32_e32 v3, v249, v3
	v_add_f32_e32 v248, v89, v105
	v_add_f32_e32 v3, v248, v3
	v_add_f32_e32 v249, v90, v106
	v_add_f32_e32 v3, v249, v3
	v_add_f32_e32 v248, v91, v107
	v_add_f32_e32 v3, v248, v3
	v_add_f32_e32 v249, v92, v108
	s_waitcnt lgkmcnt(0)
	v_mfma_f32_32x32x16_bf16 v[16:31], v[228:231], v[8:11], v[16:31]
	v_add_f32_e32 v3, v249, v3
	v_add_f32_e32 v248, v93, v109
	v_add_f32_e32 v3, v248, v3
	v_add_f32_e32 v249, v94, v110
	v_add_f32_e32 v3, v249, v3
	v_add_f32_e32 v248, v95, v111
	v_add_f32_e32 v3, v248, v3
	v_fmac_f32_e32 v3, v221, v0
	v_mov_b32_e32 v221, v3
	s_branch .LBB0_1557
